# GEMM main loop (EpiStore instantiation): per-phase s_setprio flips removed
# speedup vs baseline: 1.0001x; 1.0001x over previous
.LBB0_1171:
	s_add_i32 s73, s30, 2
	s_add_u32 s50, s26, 0x80
	s_addc_u32 s31, s27, 0
	s_add_i32 s76, 0, 0x10000
	s_cmp_eq_u32 s29, s30
	s_cselect_b32 s31, s9, s31
	s_cselect_b32 s30, s8, s50
	s_cselect_b32 s51, s25, s72
	s_cselect_b32 s50, s24, s42
	s_add_i32 s77, 0, 0x14000
	v_add_u32_e32 v102, s76, v164
	v_add_u32_e32 v167, s77, v164
	ds_read_b128 v[66:69], v102
	ds_read_b128 v[70:73], v102 offset:1024
	ds_read_b128 v[74:77], v102 offset:2048
	ds_read_b128 v[102:105], v102 offset:3072
	ds_read_b128 v[156:159], v167
	ds_read_b128 v[160:163], v167 offset:1024
	ds_read_b128 v[168:171], v167 offset:2048
	ds_read_b128 v[172:175], v167 offset:3072
	v_lshl_add_u64 v[178:179], s[26:27], 0, v[152:153]
	s_add_i32 m0, s10, 0xc000
	ds_read_b128 v[184:187], v166
	ds_read_b128 v[188:191], v166 offset:1024
	ds_read_b128 v[192:195], v166 offset:2048
	ds_read_b128 v[196:199], v166 offset:3072
	ds_read_b128 v[200:203], v166 offset:4096
	ds_read_b128 v[204:207], v166 offset:5120
	ds_read_b128 v[208:211], v166 offset:6144
	ds_read_b128 v[212:215], v166 offset:7168
	global_load_lds_dwordx4 v[178:179], off
	v_lshl_add_u64 v[178:179], s[26:27], 0, v[154:155]
	s_add_i32 m0, s10, 0xe000
	s_nop 0
	global_load_lds_dwordx4 v[178:179], off
	s_waitcnt vmcnt(8)
	s_waitcnt lgkmcnt(0)
	s_barrier
	s_waitcnt lgkmcnt(0)
	v_mfma_f32_16x16x32_bf16 v[142:145], v[66:69], v[184:187], v[142:145]
	v_mfma_f32_16x16x32_bf16 v[138:141], v[74:77], v[184:187], v[138:141]
	v_mfma_f32_16x16x32_bf16 v[134:137], v[66:69], v[192:195], v[134:137]
	v_mfma_f32_16x16x32_bf16 v[130:133], v[74:77], v[192:195], v[130:133]
	v_mfma_f32_16x16x32_bf16 v[110:113], v[66:69], v[200:203], v[110:113]
	v_mfma_f32_16x16x32_bf16 v[106:109], v[74:77], v[200:203], v[106:109]
	v_mfma_f32_16x16x32_bf16 v[98:101], v[66:69], v[208:211], v[98:101]
	v_mfma_f32_16x16x32_bf16 v[94:97], v[74:77], v[208:211], v[94:97]
	v_mfma_f32_16x16x32_bf16 v[142:145], v[70:73], v[188:191], v[142:145]
	v_mfma_f32_16x16x32_bf16 v[138:141], v[102:105], v[188:191], v[138:141]
	v_mfma_f32_16x16x32_bf16 v[134:137], v[70:73], v[196:199], v[134:137]
	v_mfma_f32_16x16x32_bf16 v[130:133], v[102:105], v[196:199], v[130:133]
	v_mfma_f32_16x16x32_bf16 v[110:113], v[70:73], v[204:207], v[110:113]
	v_mfma_f32_16x16x32_bf16 v[106:109], v[102:105], v[204:207], v[106:109]
	v_mfma_f32_16x16x32_bf16 v[98:101], v[70:73], v[212:215], v[98:101]
	v_mfma_f32_16x16x32_bf16 v[94:97], v[102:105], v[212:215], v[94:97]
	v_mfma_f32_16x16x32_bf16 v[126:129], v[156:159], v[184:187], v[126:129]
	v_mfma_f32_16x16x32_bf16 v[122:125], v[168:171], v[184:187], v[122:125]
	v_mfma_f32_16x16x32_bf16 v[118:121], v[156:159], v[192:195], v[118:121]
	v_mfma_f32_16x16x32_bf16 v[114:117], v[168:171], v[192:195], v[114:117]
	v_mfma_f32_16x16x32_bf16 v[90:93], v[156:159], v[200:203], v[90:93]
	v_mfma_f32_16x16x32_bf16 v[86:89], v[168:171], v[200:203], v[86:89]
	v_mfma_f32_16x16x32_bf16 v[82:85], v[156:159], v[208:211], v[82:85]
	v_mfma_f32_16x16x32_bf16 v[78:81], v[168:171], v[208:211], v[78:81]
	v_mfma_f32_16x16x32_bf16 v[126:129], v[160:163], v[188:191], v[126:129]
	v_mfma_f32_16x16x32_bf16 v[122:125], v[172:175], v[188:191], v[122:125]
	v_mfma_f32_16x16x32_bf16 v[118:121], v[160:163], v[196:199], v[118:121]
	v_mfma_f32_16x16x32_bf16 v[114:117], v[172:175], v[196:199], v[114:117]
	v_mfma_f32_16x16x32_bf16 v[90:93], v[160:163], v[204:207], v[90:93]
	v_mfma_f32_16x16x32_bf16 v[86:89], v[172:175], v[204:207], v[86:89]
	v_mfma_f32_16x16x32_bf16 v[82:85], v[160:163], v[212:215], v[82:85]
	v_mfma_f32_16x16x32_bf16 v[78:81], v[172:175], v[212:215], v[78:81]
	s_barrier
	s_add_i32 s76, s76, s5
	v_lshl_add_u64 v[178:179], s[50:51], 0, v[0:1]
	s_mov_b32 m0, s76
	ds_read_b128 v[184:187], v166 offset:16384
	ds_read_b128 v[188:191], v166 offset:17408
	ds_read_b128 v[192:195], v166 offset:18432
	ds_read_b128 v[196:199], v166 offset:19456
	ds_read_b128 v[200:203], v166 offset:20480
	ds_read_b128 v[204:207], v166 offset:21504
	ds_read_b128 v[208:211], v166 offset:22528
	ds_read_b128 v[212:215], v166 offset:23552
	global_load_lds_dwordx4 v[178:179], off
	s_add_i32 m0, s76, 0x2000
	v_lshl_add_u64 v[216:217], s[50:51], 0, v[150:151]
	s_add_u32 s50, s50, s54
	s_addc_u32 s51, s51, 0
	s_add_i32 s76, s77, s5
	global_load_lds_dwordx4 v[216:217], off
	v_lshl_add_u64 v[218:219], s[50:51], 0, v[0:1]
	s_mov_b32 m0, s76
	v_lshl_add_u64 v[220:221], s[50:51], 0, v[150:151]
	global_load_lds_dwordx4 v[218:219], off
	s_add_i32 m0, s76, 0x2000
	v_lshl_add_u64 v[222:223], s[30:31], 0, v[0:1]
	global_load_lds_dwordx4 v[220:221], off
	s_mov_b32 m0, s10
	v_lshl_add_u64 v[224:225], s[30:31], 0, v[150:151]
	global_load_lds_dwordx4 v[222:223], off
	s_mov_b32 m0, s11
	s_nop 0
	global_load_lds_dwordx4 v[224:225], off
	s_waitcnt vmcnt(8)
	s_waitcnt lgkmcnt(0)
	s_barrier
	s_waitcnt lgkmcnt(0)
	v_mfma_f32_16x16x32_bf16 v[62:65], v[66:69], v[184:187], v[62:65]
	v_mfma_f32_16x16x32_bf16 v[58:61], v[74:77], v[184:187], v[58:61]
	v_mfma_f32_16x16x32_bf16 v[54:57], v[66:69], v[192:195], v[54:57]
	v_mfma_f32_16x16x32_bf16 v[50:53], v[74:77], v[192:195], v[50:53]
	v_mfma_f32_16x16x32_bf16 v[30:33], v[66:69], v[200:203], v[30:33]
	v_mfma_f32_16x16x32_bf16 v[26:29], v[74:77], v[200:203], v[26:29]
	v_mfma_f32_16x16x32_bf16 v[22:25], v[66:69], v[208:211], v[22:25]
	v_mfma_f32_16x16x32_bf16 v[10:13], v[74:77], v[208:211], v[10:13]
	v_mfma_f32_16x16x32_bf16 v[62:65], v[70:73], v[188:191], v[62:65]
	v_mfma_f32_16x16x32_bf16 v[58:61], v[102:105], v[188:191], v[58:61]
	v_mfma_f32_16x16x32_bf16 v[54:57], v[70:73], v[196:199], v[54:57]
	v_mfma_f32_16x16x32_bf16 v[50:53], v[102:105], v[196:199], v[50:53]
	v_mfma_f32_16x16x32_bf16 v[30:33], v[70:73], v[204:207], v[30:33]
	v_mfma_f32_16x16x32_bf16 v[26:29], v[102:105], v[204:207], v[26:29]
	v_mfma_f32_16x16x32_bf16 v[22:25], v[70:73], v[212:215], v[22:25]
	v_mfma_f32_16x16x32_bf16 v[10:13], v[102:105], v[212:215], v[10:13]
	v_mfma_f32_16x16x32_bf16 v[46:49], v[156:159], v[184:187], v[46:49]
	v_mfma_f32_16x16x32_bf16 v[42:45], v[168:171], v[184:187], v[42:45]
	v_mfma_f32_16x16x32_bf16 v[38:41], v[156:159], v[192:195], v[38:41]
	v_mfma_f32_16x16x32_bf16 v[34:37], v[168:171], v[192:195], v[34:37]
	v_mfma_f32_16x16x32_bf16 v[18:21], v[156:159], v[200:203], v[18:21]
	v_mfma_f32_16x16x32_bf16 v[14:17], v[168:171], v[200:203], v[14:17]
	v_mfma_f32_16x16x32_bf16 v[6:9], v[156:159], v[208:211], v[6:9]
	v_mfma_f32_16x16x32_bf16 v[2:5], v[168:171], v[208:211], v[2:5]
	v_mfma_f32_16x16x32_bf16 v[46:49], v[160:163], v[188:191], v[46:49]
	v_mfma_f32_16x16x32_bf16 v[42:45], v[172:175], v[188:191], v[42:45]
	v_mfma_f32_16x16x32_bf16 v[38:41], v[160:163], v[196:199], v[38:41]
	v_mfma_f32_16x16x32_bf16 v[34:37], v[172:175], v[196:199], v[34:37]
	v_mfma_f32_16x16x32_bf16 v[18:21], v[160:163], v[204:207], v[18:21]
	v_mfma_f32_16x16x32_bf16 v[14:17], v[172:175], v[204:207], v[14:17]
	v_mfma_f32_16x16x32_bf16 v[6:9], v[160:163], v[212:215], v[6:9]
	v_mfma_f32_16x16x32_bf16 v[2:5], v[172:175], v[212:215], v[2:5]
	s_barrier
	s_add_i32 s50, 0, 0x18000
	s_add_i32 s51, 0, 0x1c000
	v_add_u32_e32 v102, s50, v164
	v_add_u32_e32 v167, s51, v164
	ds_read_b128 v[66:69], v102
	ds_read_b128 v[70:73], v102 offset:1024
	ds_read_b128 v[74:77], v102 offset:2048
	ds_read_b128 v[102:105], v102 offset:3072
	ds_read_b128 v[156:159], v167
	ds_read_b128 v[160:163], v167 offset:1024
	ds_read_b128 v[168:171], v167 offset:2048
	ds_read_b128 v[172:175], v167 offset:3072
	s_add_u32 s30, s30, s54
	s_addc_u32 s31, s31, 0
	s_mov_b32 m0, s14
	v_lshl_add_u64 v[226:227], s[30:31], 0, v[0:1]
	ds_read_b128 v[184:187], v166 offset:32768
	ds_read_b128 v[188:191], v166 offset:33792
	ds_read_b128 v[192:195], v166 offset:34816
	ds_read_b128 v[196:199], v166 offset:35840
	ds_read_b128 v[200:203], v166 offset:36864
	ds_read_b128 v[204:207], v166 offset:37888
	ds_read_b128 v[208:211], v166 offset:38912
	ds_read_b128 v[212:215], v166 offset:39936
	global_load_lds_dwordx4 v[226:227], off
	v_lshl_add_u64 v[226:227], s[30:31], 0, v[150:151]
	s_mov_b32 m0, s15
	s_nop 0
	global_load_lds_dwordx4 v[226:227], off
	s_waitcnt vmcnt(8)
	s_waitcnt lgkmcnt(0)
	s_barrier
	s_waitcnt lgkmcnt(0)
	v_mfma_f32_16x16x32_bf16 v[142:145], v[66:69], v[184:187], v[142:145]
	v_mfma_f32_16x16x32_bf16 v[138:141], v[74:77], v[184:187], v[138:141]
	v_mfma_f32_16x16x32_bf16 v[134:137], v[66:69], v[192:195], v[134:137]
	v_mfma_f32_16x16x32_bf16 v[130:133], v[74:77], v[192:195], v[130:133]
	v_mfma_f32_16x16x32_bf16 v[110:113], v[66:69], v[200:203], v[110:113]
	v_mfma_f32_16x16x32_bf16 v[106:109], v[74:77], v[200:203], v[106:109]
	v_mfma_f32_16x16x32_bf16 v[98:101], v[66:69], v[208:211], v[98:101]
	v_mfma_f32_16x16x32_bf16 v[94:97], v[74:77], v[208:211], v[94:97]
	v_mfma_f32_16x16x32_bf16 v[142:145], v[70:73], v[188:191], v[142:145]
	v_mfma_f32_16x16x32_bf16 v[138:141], v[102:105], v[188:191], v[138:141]
	v_mfma_f32_16x16x32_bf16 v[134:137], v[70:73], v[196:199], v[134:137]
	v_mfma_f32_16x16x32_bf16 v[130:133], v[102:105], v[196:199], v[130:133]
	v_mfma_f32_16x16x32_bf16 v[110:113], v[70:73], v[204:207], v[110:113]
	v_mfma_f32_16x16x32_bf16 v[106:109], v[102:105], v[204:207], v[106:109]
	v_mfma_f32_16x16x32_bf16 v[98:101], v[70:73], v[212:215], v[98:101]
	v_mfma_f32_16x16x32_bf16 v[94:97], v[102:105], v[212:215], v[94:97]
	v_mfma_f32_16x16x32_bf16 v[126:129], v[156:159], v[184:187], v[126:129]
	v_mfma_f32_16x16x32_bf16 v[122:125], v[168:171], v[184:187], v[122:125]
	v_mfma_f32_16x16x32_bf16 v[118:121], v[156:159], v[192:195], v[118:121]
	v_mfma_f32_16x16x32_bf16 v[114:117], v[168:171], v[192:195], v[114:117]
	v_mfma_f32_16x16x32_bf16 v[90:93], v[156:159], v[200:203], v[90:93]
	v_mfma_f32_16x16x32_bf16 v[86:89], v[168:171], v[200:203], v[86:89]
	v_mfma_f32_16x16x32_bf16 v[82:85], v[156:159], v[208:211], v[82:85]
	v_mfma_f32_16x16x32_bf16 v[78:81], v[168:171], v[208:211], v[78:81]
	v_mfma_f32_16x16x32_bf16 v[126:129], v[160:163], v[188:191], v[126:129]
	v_mfma_f32_16x16x32_bf16 v[122:125], v[172:175], v[188:191], v[122:125]
	v_mfma_f32_16x16x32_bf16 v[118:121], v[160:163], v[196:199], v[118:121]
	v_mfma_f32_16x16x32_bf16 v[114:117], v[172:175], v[196:199], v[114:117]
	v_mfma_f32_16x16x32_bf16 v[90:93], v[160:163], v[204:207], v[90:93]
	v_mfma_f32_16x16x32_bf16 v[86:89], v[172:175], v[204:207], v[86:89]
	v_mfma_f32_16x16x32_bf16 v[82:85], v[160:163], v[212:215], v[82:85]
	v_mfma_f32_16x16x32_bf16 v[78:81], v[172:175], v[212:215], v[78:81]
	s_barrier
	s_add_i32 s30, s50, s5
	v_lshl_add_u64 v[178:179], v[178:179], 0, s[56:57]
	s_mov_b32 m0, s30
	ds_read_b128 v[184:187], v166 offset:49152
	ds_read_b128 v[188:191], v166 offset:50176
	ds_read_b128 v[192:195], v166 offset:51200
	ds_read_b128 v[196:199], v166 offset:52224
	ds_read_b128 v[200:203], v166 offset:53248
	ds_read_b128 v[204:207], v166 offset:54272
	ds_read_b128 v[208:211], v166 offset:55296
	ds_read_b128 v[212:215], v166 offset:56320
	global_load_lds_dwordx4 v[178:179], off
	v_lshl_add_u64 v[178:179], v[216:217], 0, s[56:57]
	s_add_i32 m0, s30, 0x2000
	s_add_i32 s30, s51, s5
	global_load_lds_dwordx4 v[178:179], off
	v_lshl_add_u64 v[178:179], v[218:219], 0, s[56:57]
	s_mov_b32 m0, s30
	s_nop 0
	global_load_lds_dwordx4 v[178:179], off
	v_lshl_add_u64 v[178:179], v[220:221], 0, s[56:57]
	s_add_i32 m0, s30, 0x2000
	s_nop 0
	global_load_lds_dwordx4 v[178:179], off
	v_lshl_add_u64 v[178:179], v[222:223], 0, s[56:57]
	s_mov_b32 m0, s17
	s_nop 0
	global_load_lds_dwordx4 v[178:179], off
	v_lshl_add_u64 v[178:179], v[224:225], 0, s[56:57]
	s_mov_b32 m0, s28
	s_nop 0
	global_load_lds_dwordx4 v[178:179], off
	s_waitcnt vmcnt(8)
	s_waitcnt lgkmcnt(0)
	s_barrier
	s_waitcnt lgkmcnt(0)
	v_mfma_f32_16x16x32_bf16 v[62:65], v[66:69], v[184:187], v[62:65]
	v_mfma_f32_16x16x32_bf16 v[58:61], v[74:77], v[184:187], v[58:61]
	v_mfma_f32_16x16x32_bf16 v[54:57], v[66:69], v[192:195], v[54:57]
	v_mfma_f32_16x16x32_bf16 v[50:53], v[74:77], v[192:195], v[50:53]
	v_mfma_f32_16x16x32_bf16 v[30:33], v[66:69], v[200:203], v[30:33]
	v_mfma_f32_16x16x32_bf16 v[26:29], v[74:77], v[200:203], v[26:29]
	v_mfma_f32_16x16x32_bf16 v[22:25], v[66:69], v[208:211], v[22:25]
	v_mfma_f32_16x16x32_bf16 v[10:13], v[74:77], v[208:211], v[10:13]
	v_mfma_f32_16x16x32_bf16 v[62:65], v[70:73], v[188:191], v[62:65]
	v_mfma_f32_16x16x32_bf16 v[58:61], v[102:105], v[188:191], v[58:61]
	v_mfma_f32_16x16x32_bf16 v[54:57], v[70:73], v[196:199], v[54:57]
	v_mfma_f32_16x16x32_bf16 v[50:53], v[102:105], v[196:199], v[50:53]
	v_mfma_f32_16x16x32_bf16 v[30:33], v[70:73], v[204:207], v[30:33]
	v_mfma_f32_16x16x32_bf16 v[26:29], v[102:105], v[204:207], v[26:29]
	v_mfma_f32_16x16x32_bf16 v[22:25], v[70:73], v[212:215], v[22:25]
	v_mfma_f32_16x16x32_bf16 v[10:13], v[102:105], v[212:215], v[10:13]
	v_mfma_f32_16x16x32_bf16 v[46:49], v[156:159], v[184:187], v[46:49]
	v_mfma_f32_16x16x32_bf16 v[42:45], v[168:171], v[184:187], v[42:45]
	v_mfma_f32_16x16x32_bf16 v[38:41], v[156:159], v[192:195], v[38:41]
	v_mfma_f32_16x16x32_bf16 v[34:37], v[168:171], v[192:195], v[34:37]
	v_mfma_f32_16x16x32_bf16 v[18:21], v[156:159], v[200:203], v[18:21]
	v_mfma_f32_16x16x32_bf16 v[14:17], v[168:171], v[200:203], v[14:17]
	v_mfma_f32_16x16x32_bf16 v[6:9], v[156:159], v[208:211], v[6:9]
	v_mfma_f32_16x16x32_bf16 v[2:5], v[168:171], v[208:211], v[2:5]
	v_mfma_f32_16x16x32_bf16 v[46:49], v[160:163], v[188:191], v[46:49]
	v_mfma_f32_16x16x32_bf16 v[42:45], v[172:175], v[188:191], v[42:45]
	v_mfma_f32_16x16x32_bf16 v[38:41], v[160:163], v[196:199], v[38:41]
	v_mfma_f32_16x16x32_bf16 v[34:37], v[172:175], v[196:199], v[34:37]
	v_mfma_f32_16x16x32_bf16 v[18:21], v[160:163], v[204:207], v[18:21]
	v_mfma_f32_16x16x32_bf16 v[14:17], v[172:175], v[204:207], v[14:17]
	v_mfma_f32_16x16x32_bf16 v[6:9], v[160:163], v[212:215], v[6:9]
	v_mfma_f32_16x16x32_bf16 v[2:5], v[172:175], v[212:215], v[2:5]
	s_barrier
	s_add_u32 s26, s26, 0x100
	s_addc_u32 s27, s27, 0
	s_add_u32 s42, s42, 0x100
	s_addc_u32 s72, s72, 0
	s_cmp_ge_u32 s73, s16
	s_mov_b32 s30, s73
	s_cbranch_scc0 .LBB0_1171
	s_and_b64 vcc, exec, s[22:23]
	s_cbranch_vccz .LBB0_1174
	s_barrier
